# rstd prefill: ssq rows of all units of a half-workgroup loaded in one batch (one wait) instead of one round trip per unit
# baseline (speedup 1.0000x reference)
.Lrstd1_outer:
	s_mov_b32 s22, 0
	v_cmp_gt_i64_e32 vcc, s[12:13], v[168:169]
	s_cbranch_vccnz .Lrstd1_issued
	s_ashr_i32 s14, s12, 31
	s_lshr_b32 s14, s14, 29
	s_add_i32 s14, s12, s14
	s_ashr_i32 s15, s14, 3
	s_and_b32 s14, s14, -8
	s_sub_i32 s14, s12, s14
	s_cmp_lt_i32 s14, 0
	s_movk_i32 s16, 0xa1
	s_cselect_b32 s16, s16, 0xa0
	s_mul_i32 s14, s14, s16
	s_add_i32 s14, s14, s15
	s_mul_hi_i32 s15, s14, 0x66666667
	s_lshr_b32 s16, s15, 31
	s_ashr_i32 s15, s15, 5
	s_add_i32 s15, s15, s16
	s_lshl_b32 s16, s15, 3
	s_sub_i32 s17, 0x80, s16
	s_min_i32 s17, s17, 8
	s_abs_i32 s17, s17
	v_cvt_f32_u32_e32 v3, s17
	s_sub_i32 s18, 0, s17
	s_mulk_i32 s15, 0x50
	s_sub_i32 s14, s14, s15
	v_rcp_iflag_f32_e32 v3, v3
	s_ashr_i32 s15, s14, 31
	s_abs_i32 s14, s14
	v_mul_f32_e32 v3, 0x4f7ffffe, v3
	v_cvt_u32_f32_e32 v3, v3
	s_nop 0
	v_readfirstlane_b32 s19, v3
	s_mul_i32 s18, s18, s19
	s_mul_hi_u32 s18, s19, s18
	s_add_i32 s19, s19, s18
	s_mul_hi_u32 s18, s14, s19
	s_mul_i32 s18, s18, s17
	s_sub_i32 s14, s14, s18
	s_sub_i32 s18, s14, s17
	s_cmp_ge_u32 s14, s17
	s_cselect_b32 s14, s18, s14
	s_sub_i32 s18, s14, s17
	s_cmp_ge_u32 s14, s17
	s_cselect_b32 s14, s18, s14
	s_xor_b32 s14, s14, s15
	s_sub_i32 s14, s14, s15
	s_add_i32 s16, s16, s14
	v_lshl_add_u32 v4, s16, 8, v0
	v_ashrrev_i32_e32 v5, 31, v4
	v_lshlrev_b64 v[4:5], 6, v[4:5]
	v_lshl_add_u64 v[4:5], s[10:11], 0, v[4:5]
	global_load_dwordx4 v[24:27], v[4:5], off
	global_load_dwordx4 v[28:31], v[4:5], off offset:32
	global_load_dwordx4 v[32:35], v[4:5], off offset:16
	global_load_dwordx4 v[36:39], v[4:5], off offset:48
	s_add_u32 s12, s12, s86
	s_addc_u32 s13, s13, s87
	s_add_u32 s12, s12, s86
	s_addc_u32 s13, s13, s87
	s_add_i32 s22, s22, 1
	v_cmp_gt_i64_e32 vcc, s[12:13], v[168:169]
	s_cbranch_vccnz .Lrstd1_issued
	s_ashr_i32 s14, s12, 31
	s_lshr_b32 s14, s14, 29
	s_add_i32 s14, s12, s14
	s_ashr_i32 s15, s14, 3
	s_and_b32 s14, s14, -8
	s_sub_i32 s14, s12, s14
	s_cmp_lt_i32 s14, 0
	s_movk_i32 s16, 0xa1
	s_cselect_b32 s16, s16, 0xa0
	s_mul_i32 s14, s14, s16
	s_add_i32 s14, s14, s15
	s_mul_hi_i32 s15, s14, 0x66666667
	s_lshr_b32 s16, s15, 31
	s_ashr_i32 s15, s15, 5
	s_add_i32 s15, s15, s16
	s_lshl_b32 s16, s15, 3
	s_sub_i32 s17, 0x80, s16
	s_min_i32 s17, s17, 8
	s_abs_i32 s17, s17
	v_cvt_f32_u32_e32 v3, s17
	s_sub_i32 s18, 0, s17
	s_mulk_i32 s15, 0x50
	s_sub_i32 s14, s14, s15
	v_rcp_iflag_f32_e32 v3, v3
	s_ashr_i32 s15, s14, 31
	s_abs_i32 s14, s14
	v_mul_f32_e32 v3, 0x4f7ffffe, v3
	v_cvt_u32_f32_e32 v3, v3
	s_nop 0
	v_readfirstlane_b32 s19, v3
	s_mul_i32 s18, s18, s19
	s_mul_hi_u32 s18, s19, s18
	s_add_i32 s19, s19, s18
	s_mul_hi_u32 s18, s14, s19
	s_mul_i32 s18, s18, s17
	s_sub_i32 s14, s14, s18
	s_sub_i32 s18, s14, s17
	s_cmp_ge_u32 s14, s17
	s_cselect_b32 s14, s18, s14
	s_sub_i32 s18, s14, s17
	s_cmp_ge_u32 s14, s17
	s_cselect_b32 s14, s18, s14
	s_xor_b32 s14, s14, s15
	s_sub_i32 s14, s14, s15
	s_add_i32 s16, s16, s14
	v_lshl_add_u32 v4, s16, 8, v0
	v_ashrrev_i32_e32 v5, 31, v4
	v_lshlrev_b64 v[4:5], 6, v[4:5]
	v_lshl_add_u64 v[4:5], s[10:11], 0, v[4:5]
	global_load_dwordx4 v[40:43], v[4:5], off
	global_load_dwordx4 v[44:47], v[4:5], off offset:32
	global_load_dwordx4 v[48:51], v[4:5], off offset:16
	global_load_dwordx4 v[52:55], v[4:5], off offset:48
	s_add_u32 s12, s12, s86
	s_addc_u32 s13, s13, s87
	s_add_u32 s12, s12, s86
	s_addc_u32 s13, s13, s87
	s_add_i32 s22, s22, 1
	v_cmp_gt_i64_e32 vcc, s[12:13], v[168:169]
	s_cbranch_vccnz .Lrstd1_issued
	s_ashr_i32 s14, s12, 31
	s_lshr_b32 s14, s14, 29
	s_add_i32 s14, s12, s14
	s_ashr_i32 s15, s14, 3
	s_and_b32 s14, s14, -8
	s_sub_i32 s14, s12, s14
	s_cmp_lt_i32 s14, 0
	s_movk_i32 s16, 0xa1
	s_cselect_b32 s16, s16, 0xa0
	s_mul_i32 s14, s14, s16
	s_add_i32 s14, s14, s15
	s_mul_hi_i32 s15, s14, 0x66666667
	s_lshr_b32 s16, s15, 31
	s_ashr_i32 s15, s15, 5
	s_add_i32 s15, s15, s16
	s_lshl_b32 s16, s15, 3
	s_sub_i32 s17, 0x80, s16
	s_min_i32 s17, s17, 8
	s_abs_i32 s17, s17
	v_cvt_f32_u32_e32 v3, s17
	s_sub_i32 s18, 0, s17
	s_mulk_i32 s15, 0x50
	s_sub_i32 s14, s14, s15
	v_rcp_iflag_f32_e32 v3, v3
	s_ashr_i32 s15, s14, 31
	s_abs_i32 s14, s14
	v_mul_f32_e32 v3, 0x4f7ffffe, v3
	v_cvt_u32_f32_e32 v3, v3
	s_nop 0
	v_readfirstlane_b32 s19, v3
	s_mul_i32 s18, s18, s19
	s_mul_hi_u32 s18, s19, s18
	s_add_i32 s19, s19, s18
	s_mul_hi_u32 s18, s14, s19
	s_mul_i32 s18, s18, s17
	s_sub_i32 s14, s14, s18
	s_sub_i32 s18, s14, s17
	s_cmp_ge_u32 s14, s17
	s_cselect_b32 s14, s18, s14
	s_sub_i32 s18, s14, s17
	s_cmp_ge_u32 s14, s17
	s_cselect_b32 s14, s18, s14
	s_xor_b32 s14, s14, s15
	s_sub_i32 s14, s14, s15
	s_add_i32 s16, s16, s14
	v_lshl_add_u32 v4, s16, 8, v0
	v_ashrrev_i32_e32 v5, 31, v4
	v_lshlrev_b64 v[4:5], 6, v[4:5]
	v_lshl_add_u64 v[4:5], s[10:11], 0, v[4:5]
	global_load_dwordx4 v[56:59], v[4:5], off
	global_load_dwordx4 v[60:63], v[4:5], off offset:32
	global_load_dwordx4 v[64:67], v[4:5], off offset:16
	global_load_dwordx4 v[68:71], v[4:5], off offset:48
	s_add_u32 s12, s12, s86
	s_addc_u32 s13, s13, s87
	s_add_u32 s12, s12, s86
	s_addc_u32 s13, s13, s87
	s_add_i32 s22, s22, 1
	v_cmp_gt_i64_e32 vcc, s[12:13], v[168:169]
	s_cbranch_vccnz .Lrstd1_issued
	s_ashr_i32 s14, s12, 31
	s_lshr_b32 s14, s14, 29
	s_add_i32 s14, s12, s14
	s_ashr_i32 s15, s14, 3
	s_and_b32 s14, s14, -8
	s_sub_i32 s14, s12, s14
	s_cmp_lt_i32 s14, 0
	s_movk_i32 s16, 0xa1
	s_cselect_b32 s16, s16, 0xa0
	s_mul_i32 s14, s14, s16
	s_add_i32 s14, s14, s15
	s_mul_hi_i32 s15, s14, 0x66666667
	s_lshr_b32 s16, s15, 31
	s_ashr_i32 s15, s15, 5
	s_add_i32 s15, s15, s16
	s_lshl_b32 s16, s15, 3
	s_sub_i32 s17, 0x80, s16
	s_min_i32 s17, s17, 8
	s_abs_i32 s17, s17
	v_cvt_f32_u32_e32 v3, s17
	s_sub_i32 s18, 0, s17
	s_mulk_i32 s15, 0x50
	s_sub_i32 s14, s14, s15
	v_rcp_iflag_f32_e32 v3, v3
	s_ashr_i32 s15, s14, 31
	s_abs_i32 s14, s14
	v_mul_f32_e32 v3, 0x4f7ffffe, v3
	v_cvt_u32_f32_e32 v3, v3
	s_nop 0
	v_readfirstlane_b32 s19, v3
	s_mul_i32 s18, s18, s19
	s_mul_hi_u32 s18, s19, s18
	s_add_i32 s19, s19, s18
	s_mul_hi_u32 s18, s14, s19
	s_mul_i32 s18, s18, s17
	s_sub_i32 s14, s14, s18
	s_sub_i32 s18, s14, s17
	s_cmp_ge_u32 s14, s17
	s_cselect_b32 s14, s18, s14
	s_sub_i32 s18, s14, s17
	s_cmp_ge_u32 s14, s17
	s_cselect_b32 s14, s18, s14
	s_xor_b32 s14, s14, s15
	s_sub_i32 s14, s14, s15
	s_add_i32 s16, s16, s14
	v_lshl_add_u32 v4, s16, 8, v0
	v_ashrrev_i32_e32 v5, 31, v4
	v_lshlrev_b64 v[4:5], 6, v[4:5]
	v_lshl_add_u64 v[4:5], s[10:11], 0, v[4:5]
	global_load_dwordx4 v[72:75], v[4:5], off
	global_load_dwordx4 v[76:79], v[4:5], off offset:32
	global_load_dwordx4 v[80:83], v[4:5], off offset:16
	global_load_dwordx4 v[84:87], v[4:5], off offset:48
	s_add_u32 s12, s12, s86
	s_addc_u32 s13, s13, s87
	s_add_u32 s12, s12, s86
	s_addc_u32 s13, s13, s87
	s_add_i32 s22, s22, 1
	v_cmp_gt_i64_e32 vcc, s[12:13], v[168:169]
	s_cbranch_vccnz .Lrstd1_issued
	s_ashr_i32 s14, s12, 31
	s_lshr_b32 s14, s14, 29
	s_add_i32 s14, s12, s14
	s_ashr_i32 s15, s14, 3
	s_and_b32 s14, s14, -8
	s_sub_i32 s14, s12, s14
	s_cmp_lt_i32 s14, 0
	s_movk_i32 s16, 0xa1
	s_cselect_b32 s16, s16, 0xa0
	s_mul_i32 s14, s14, s16
	s_add_i32 s14, s14, s15
	s_mul_hi_i32 s15, s14, 0x66666667
	s_lshr_b32 s16, s15, 31
	s_ashr_i32 s15, s15, 5
	s_add_i32 s15, s15, s16
	s_lshl_b32 s16, s15, 3
	s_sub_i32 s17, 0x80, s16
	s_min_i32 s17, s17, 8
	s_abs_i32 s17, s17
	v_cvt_f32_u32_e32 v3, s17
	s_sub_i32 s18, 0, s17
	s_mulk_i32 s15, 0x50
	s_sub_i32 s14, s14, s15
	v_rcp_iflag_f32_e32 v3, v3
	s_ashr_i32 s15, s14, 31
	s_abs_i32 s14, s14
	v_mul_f32_e32 v3, 0x4f7ffffe, v3
	v_cvt_u32_f32_e32 v3, v3
	s_nop 0
	v_readfirstlane_b32 s19, v3
	s_mul_i32 s18, s18, s19
	s_mul_hi_u32 s18, s19, s18
	s_add_i32 s19, s19, s18
	s_mul_hi_u32 s18, s14, s19
	s_mul_i32 s18, s18, s17
	s_sub_i32 s14, s14, s18
	s_sub_i32 s18, s14, s17
	s_cmp_ge_u32 s14, s17
	s_cselect_b32 s14, s18, s14
	s_sub_i32 s18, s14, s17
	s_cmp_ge_u32 s14, s17
	s_cselect_b32 s14, s18, s14
	s_xor_b32 s14, s14, s15
	s_sub_i32 s14, s14, s15
	s_add_i32 s16, s16, s14
	v_lshl_add_u32 v4, s16, 8, v0
	v_ashrrev_i32_e32 v5, 31, v4
	v_lshlrev_b64 v[4:5], 6, v[4:5]
	v_lshl_add_u64 v[4:5], s[10:11], 0, v[4:5]
	global_load_dwordx4 v[88:91], v[4:5], off
	global_load_dwordx4 v[92:95], v[4:5], off offset:32
	global_load_dwordx4 v[96:99], v[4:5], off offset:16
	global_load_dwordx4 v[100:103], v[4:5], off offset:48
	s_add_u32 s12, s12, s86
	s_addc_u32 s13, s13, s87
	s_add_u32 s12, s12, s86
	s_addc_u32 s13, s13, s87
	s_add_i32 s22, s22, 1
	v_cmp_gt_i64_e32 vcc, s[12:13], v[168:169]
	s_cbranch_vccnz .Lrstd1_issued
	s_ashr_i32 s14, s12, 31
	s_lshr_b32 s14, s14, 29
	s_add_i32 s14, s12, s14
	s_ashr_i32 s15, s14, 3
	s_and_b32 s14, s14, -8
	s_sub_i32 s14, s12, s14
	s_cmp_lt_i32 s14, 0
	s_movk_i32 s16, 0xa1
	s_cselect_b32 s16, s16, 0xa0
	s_mul_i32 s14, s14, s16
	s_add_i32 s14, s14, s15
	s_mul_hi_i32 s15, s14, 0x66666667
	s_lshr_b32 s16, s15, 31
	s_ashr_i32 s15, s15, 5
	s_add_i32 s15, s15, s16
	s_lshl_b32 s16, s15, 3
	s_sub_i32 s17, 0x80, s16
	s_min_i32 s17, s17, 8
	s_abs_i32 s17, s17
	v_cvt_f32_u32_e32 v3, s17
	s_sub_i32 s18, 0, s17
	s_mulk_i32 s15, 0x50
	s_sub_i32 s14, s14, s15
	v_rcp_iflag_f32_e32 v3, v3
	s_ashr_i32 s15, s14, 31
	s_abs_i32 s14, s14
	v_mul_f32_e32 v3, 0x4f7ffffe, v3
	v_cvt_u32_f32_e32 v3, v3
	s_nop 0
	v_readfirstlane_b32 s19, v3
	s_mul_i32 s18, s18, s19
	s_mul_hi_u32 s18, s19, s18
	s_add_i32 s19, s19, s18
	s_mul_hi_u32 s18, s14, s19
	s_mul_i32 s18, s18, s17
	s_sub_i32 s14, s14, s18
	s_sub_i32 s18, s14, s17
	s_cmp_ge_u32 s14, s17
	s_cselect_b32 s14, s18, s14
	s_sub_i32 s18, s14, s17
	s_cmp_ge_u32 s14, s17
	s_cselect_b32 s14, s18, s14
	s_xor_b32 s14, s14, s15
	s_sub_i32 s14, s14, s15
	s_add_i32 s16, s16, s14
	v_lshl_add_u32 v4, s16, 8, v0
	v_ashrrev_i32_e32 v5, 31, v4
	v_lshlrev_b64 v[4:5], 6, v[4:5]
	v_lshl_add_u64 v[4:5], s[10:11], 0, v[4:5]
	global_load_dwordx4 v[104:107], v[4:5], off
	global_load_dwordx4 v[108:111], v[4:5], off offset:32
	global_load_dwordx4 v[112:115], v[4:5], off offset:16
	global_load_dwordx4 v[116:119], v[4:5], off offset:48
	s_add_u32 s12, s12, s86
	s_addc_u32 s13, s13, s87
	s_add_u32 s12, s12, s86
	s_addc_u32 s13, s13, s87
	s_add_i32 s22, s22, 1
.Lrstd1_issued:
	s_waitcnt vmcnt(0)
	s_cmp_le_u32 s22, 0
	s_cbranch_scc1 .Lrstd1_done
	v_add_f32_e32 v24, v24, v25
	v_add_f32_e32 v26, v26, v27
	v_add_f32_e32 v28, v28, v29
	v_add_f32_e32 v30, v30, v31
	v_add_f32_e32 v32, v32, v33
	v_add_f32_e32 v34, v34, v35
	v_add_f32_e32 v36, v36, v37
	v_add_f32_e32 v38, v38, v39
	v_add_f32_e32 v24, v24, v26
	v_add_f32_e32 v28, v28, v30
	v_add_f32_e32 v32, v32, v34
	v_add_f32_e32 v36, v36, v38
	v_add_f32_e32 v24, v24, v32
	v_add_f32_e32 v28, v28, v36
	v_add_f32_e32 v3, v24, v28
	v_fmamk_f32 v3, v3, 0x3a800000, v209
	v_mul_f32_e32 v4, 0x4b800000, v3
	v_cmp_gt_f32_e32 vcc, s68, v3
	s_nop 1
	v_cndmask_b32_e32 v3, v3, v4, vcc
	v_rsq_f32_e32 v3, v3
	s_nop 0
	v_mul_f32_e32 v4, 0x45800000, v3
	v_cndmask_b32_e32 v3, v3, v4, vcc
	ds_write_b32 v1, v3
	v_add_u32_e32 v1, 0x800, v1
	s_cmp_le_u32 s22, 1
	s_cbranch_scc1 .Lrstd1_done
	v_add_f32_e32 v40, v40, v41
	v_add_f32_e32 v42, v42, v43
	v_add_f32_e32 v44, v44, v45
	v_add_f32_e32 v46, v46, v47
	v_add_f32_e32 v48, v48, v49
	v_add_f32_e32 v50, v50, v51
	v_add_f32_e32 v52, v52, v53
	v_add_f32_e32 v54, v54, v55
	v_add_f32_e32 v40, v40, v42
	v_add_f32_e32 v44, v44, v46
	v_add_f32_e32 v48, v48, v50
	v_add_f32_e32 v52, v52, v54
	v_add_f32_e32 v40, v40, v48
	v_add_f32_e32 v44, v44, v52
	v_add_f32_e32 v3, v40, v44
	v_fmamk_f32 v3, v3, 0x3a800000, v209
	v_mul_f32_e32 v4, 0x4b800000, v3
	v_cmp_gt_f32_e32 vcc, s68, v3
	s_nop 1
	v_cndmask_b32_e32 v3, v3, v4, vcc
	v_rsq_f32_e32 v3, v3
	s_nop 0
	v_mul_f32_e32 v4, 0x45800000, v3
	v_cndmask_b32_e32 v3, v3, v4, vcc
	ds_write_b32 v1, v3
	v_add_u32_e32 v1, 0x800, v1
	s_cmp_le_u32 s22, 2
	s_cbranch_scc1 .Lrstd1_done
	v_add_f32_e32 v56, v56, v57
	v_add_f32_e32 v58, v58, v59
	v_add_f32_e32 v60, v60, v61
	v_add_f32_e32 v62, v62, v63
	v_add_f32_e32 v64, v64, v65
	v_add_f32_e32 v66, v66, v67
	v_add_f32_e32 v68, v68, v69
	v_add_f32_e32 v70, v70, v71
	v_add_f32_e32 v56, v56, v58
	v_add_f32_e32 v60, v60, v62
	v_add_f32_e32 v64, v64, v66
	v_add_f32_e32 v68, v68, v70
	v_add_f32_e32 v56, v56, v64
	v_add_f32_e32 v60, v60, v68
	v_add_f32_e32 v3, v56, v60
	v_fmamk_f32 v3, v3, 0x3a800000, v209
	v_mul_f32_e32 v4, 0x4b800000, v3
	v_cmp_gt_f32_e32 vcc, s68, v3
	s_nop 1
	v_cndmask_b32_e32 v3, v3, v4, vcc
	v_rsq_f32_e32 v3, v3
	s_nop 0
	v_mul_f32_e32 v4, 0x45800000, v3
	v_cndmask_b32_e32 v3, v3, v4, vcc
	ds_write_b32 v1, v3
	v_add_u32_e32 v1, 0x800, v1
	s_cmp_le_u32 s22, 3
	s_cbranch_scc1 .Lrstd1_done
	v_add_f32_e32 v72, v72, v73
	v_add_f32_e32 v74, v74, v75
	v_add_f32_e32 v76, v76, v77
	v_add_f32_e32 v78, v78, v79
	v_add_f32_e32 v80, v80, v81
	v_add_f32_e32 v82, v82, v83
	v_add_f32_e32 v84, v84, v85
	v_add_f32_e32 v86, v86, v87
	v_add_f32_e32 v72, v72, v74
	v_add_f32_e32 v76, v76, v78
	v_add_f32_e32 v80, v80, v82
	v_add_f32_e32 v84, v84, v86
	v_add_f32_e32 v72, v72, v80
	v_add_f32_e32 v76, v76, v84
	v_add_f32_e32 v3, v72, v76
	v_fmamk_f32 v3, v3, 0x3a800000, v209
	v_mul_f32_e32 v4, 0x4b800000, v3
	v_cmp_gt_f32_e32 vcc, s68, v3
	s_nop 1
	v_cndmask_b32_e32 v3, v3, v4, vcc
	v_rsq_f32_e32 v3, v3
	s_nop 0
	v_mul_f32_e32 v4, 0x45800000, v3
	v_cndmask_b32_e32 v3, v3, v4, vcc
	ds_write_b32 v1, v3
	v_add_u32_e32 v1, 0x800, v1
	s_cmp_le_u32 s22, 4
	s_cbranch_scc1 .Lrstd1_done
	v_add_f32_e32 v88, v88, v89
	v_add_f32_e32 v90, v90, v91
	v_add_f32_e32 v92, v92, v93
	v_add_f32_e32 v94, v94, v95
	v_add_f32_e32 v96, v96, v97
	v_add_f32_e32 v98, v98, v99
	v_add_f32_e32 v100, v100, v101
	v_add_f32_e32 v102, v102, v103
	v_add_f32_e32 v88, v88, v90
	v_add_f32_e32 v92, v92, v94
	v_add_f32_e32 v96, v96, v98
	v_add_f32_e32 v100, v100, v102
	v_add_f32_e32 v88, v88, v96
	v_add_f32_e32 v92, v92, v100
	v_add_f32_e32 v3, v88, v92
	v_fmamk_f32 v3, v3, 0x3a800000, v209
	v_mul_f32_e32 v4, 0x4b800000, v3
	v_cmp_gt_f32_e32 vcc, s68, v3
	s_nop 1
	v_cndmask_b32_e32 v3, v3, v4, vcc
	v_rsq_f32_e32 v3, v3
	s_nop 0
	v_mul_f32_e32 v4, 0x45800000, v3
	v_cndmask_b32_e32 v3, v3, v4, vcc
	ds_write_b32 v1, v3
	v_add_u32_e32 v1, 0x800, v1
	s_cmp_le_u32 s22, 5
	s_cbranch_scc1 .Lrstd1_done
	v_add_f32_e32 v104, v104, v105
	v_add_f32_e32 v106, v106, v107
	v_add_f32_e32 v108, v108, v109
	v_add_f32_e32 v110, v110, v111
	v_add_f32_e32 v112, v112, v113
	v_add_f32_e32 v114, v114, v115
	v_add_f32_e32 v116, v116, v117
	v_add_f32_e32 v118, v118, v119
	v_add_f32_e32 v104, v104, v106
	v_add_f32_e32 v108, v108, v110
	v_add_f32_e32 v112, v112, v114
	v_add_f32_e32 v116, v116, v118
	v_add_f32_e32 v104, v104, v112
	v_add_f32_e32 v108, v108, v116
	v_add_f32_e32 v3, v104, v108
	v_fmamk_f32 v3, v3, 0x3a800000, v209
	v_mul_f32_e32 v4, 0x4b800000, v3
	v_cmp_gt_f32_e32 vcc, s68, v3
	s_nop 1
	v_cndmask_b32_e32 v3, v3, v4, vcc
	v_rsq_f32_e32 v3, v3
	s_nop 0
	v_mul_f32_e32 v4, 0x45800000, v3
	v_cndmask_b32_e32 v3, v3, v4, vcc
	ds_write_b32 v1, v3
	v_add_u32_e32 v1, 0x800, v1
	s_branch .Lrstd1_outer
.Lrstd1_done:
.LBB0_138:
	s_or_b64 exec, exec, s[8:9]
	v_writelane_b32 v253, s20, 5
	s_xor_b64 s[8:9], s[20:21], -1
	s_mov_b32 s37, s95
	v_writelane_b32 v253, s21, 6
	v_writelane_b32 v253, s8, 7
	s_mov_b64 s[12:13], s[84:85]
	v_mov_b32_e32 v12, v208
	v_writelane_b32 v253, s9, 8
	v_readlane_b32 s8, v254, 3
	v_readlane_b32 s9, v254, 4
	s_waitcnt lgkmcnt(0)
	s_barrier
	s_and_b64 vcc, exec, s[8:9]
	v_readfirstlane_b32 s20, v12
	v_writelane_b32 v253, s36, 9
	s_nop 1
	v_writelane_b32 v253, s37, 10
	s_cbranch_vccz .LBB0_378
	v_lshlrev_b32_e32 v1, 4, v12
	v_add_u32_e32 v0, 0x2000, v1
	v_ashrrev_i32_e32 v3, 31, v0
	v_lshrrev_b32_e32 v3, 22, v3
	v_add_u32_e32 v3, v0, v3
	v_ashrrev_i32_e32 v13, 10, v3
	v_mul_i32_i24_e32 v3, 0x400, v13
	v_sub_u32_e32 v0, v0, v3
	v_lshrrev_b32_e32 v3, 4, v0
	v_bitop3_b32 v0, v3, v0, 32 bitop3:0x6c
	v_ashrrev_i32_e32 v3, 31, v0
	s_ashr_i32 s21, s20, 6
	v_lshrrev_b32_e32 v3, 26, v3
	s_ashr_i32 s22, s20, 8
	s_lshl_b32 s38, s21, 10
	v_add_u32_e32 v3, v0, v3
	v_lshlrev_b32_e32 v4, 3, v13
	s_add_u32 s39, s6, 0x3e00000
	v_ashrrev_i32_e32 v14, 6, v3
	v_and_b32_e32 v4, -16, v4
	s_addc_u32 s40, s7, 0
	s_mul_i32 s8, s36, 0x500000
	v_add_u32_e32 v4, v14, v4
	s_add_u32 s41, s6, s8
	v_and_b32_e32 v5, 3, v14
	s_mov_b32 s8, 0x1fffe0
	v_lshrrev_b32_e32 v6, 2, v4
	v_lshlrev_b32_e32 v7, 1, v4
	v_and_b32_e32 v3, 0xc0, v3
	v_and_or_b32 v5, v4, s8, v5
	v_and_b32_e32 v6, 4, v6
	v_and_b32_e32 v7, 24, v7
	v_sub_u32_e32 v0, v0, v3
	v_or3_b32 v5, v5, v6, v7
	v_lshlrev_b32_e32 v6, 5, v13
	v_ashrrev_i16_sdwa v0, v210, sext(v0) dst_sel:DWORD dst_unused:UNUSED_PAD src0_sel:DWORD src1_sel:BYTE_0
	v_and_b32_e32 v6, 32, v6
	v_bfe_i32 v15, v0, 0, 16
	v_add_lshl_u32 v3, v6, v15, 1
	v_lshl_add_u32 v0, v5, 11, v3
	v_lshl_add_u32 v140, v4, 11, v3
	v_bfe_i32 v3, v12, 27, 1
	v_lshrrev_b32_e32 v3, 22, v3
	v_add_u32_e32 v3, v1, v3
	v_and_b32_e32 v3, 0xfffffc00, v3
	v_sub_u32_e32 v1, v1, v3
	v_lshrrev_b32_e32 v3, 4, v1
	v_ashrrev_i32_e32 v4, 31, v12
	v_bitop3_b32 v1, v3, v1, 32 bitop3:0x6c
	v_lshrrev_b32_e32 v4, 26, v4
	v_ashrrev_i32_e32 v3, 31, v1
	v_add_u32_e32 v4, v12, v4
	v_lshrrev_b32_e32 v3, 26, v3
	v_ashrrev_i32_e32 v17, 6, v4
	v_add_u32_e32 v3, v1, v3
	v_lshlrev_b32_e32 v4, 3, v17
	v_ashrrev_i32_e32 v16, 6, v3
	v_and_b32_e32 v4, -16, v4
	v_add_u32_e32 v4, v16, v4
	v_and_b32_e32 v5, 3, v16
	v_lshrrev_b32_e32 v6, 2, v4
	v_lshlrev_b32_e32 v7, 1, v4
	v_and_b32_e32 v3, 0xc0, v3
	v_and_or_b32 v5, v4, s8, v5
	v_and_b32_e32 v6, 4, v6
	v_and_b32_e32 v7, 24, v7
	v_sub_u32_e32 v1, v1, v3
	s_addc_u32 s42, s7, 0
	v_or3_b32 v5, v5, v6, v7
	v_lshlrev_b32_e32 v6, 5, v17
	v_ashrrev_i16_sdwa v1, v210, sext(v1) dst_sel:DWORD dst_unused:UNUSED_PAD src0_sel:DWORD src1_sel:BYTE_0
	v_readlane_b32 s8, v254, 25
	v_and_b32_e32 v6, 32, v6
	v_bfe_i32 v18, v1, 0, 16
	v_readlane_b32 s9, v254, 26
	s_add_u32 s10, s41, s8
	v_add_lshl_u32 v1, v6, v18, 1
	s_addc_u32 s11, s42, s9
	s_add_i32 s43, s38, 0
	v_lshl_add_u32 v142, v5, 11, v1
	s_add_i32 m0, s43, 0x10000
	v_lshl_add_u32 v144, v4, 11, v1
	global_load_lds_dwordx4 v142, s[10:11]
	s_add_i32 m0, s43, 0x12000
	s_add_u32 s8, s10, 0x40000
	global_load_lds_dwordx4 v0, s[10:11]
	s_addc_u32 s9, s11, 0
	s_add_i32 m0, s43, 0x14000
	s_load_dwordx2 s[18:19], s[12:13], 0x20
	global_load_lds_dwordx4 v142, s[8:9]
	s_add_i32 m0, s43, 0x16000
	v_mov_b32_e32 v143, v2
	global_load_lds_dwordx4 v0, s[8:9]
	v_readlane_b32 s8, v254, 23
	v_readlane_b32 s9, v254, 24
	s_add_u32 s8, s39, s8
	s_addc_u32 s9, s40, s9
	s_add_i32 s44, s43, 0x2000
	s_mov_b32 m0, s43
	s_add_u32 s14, s8, 0x40000
	global_load_lds_dwordx4 v144, s[8:9]
	s_mov_b32 m0, s44
	s_addc_u32 s15, s9, 0
	s_add_i32 s45, s43, 0x4000
	global_load_lds_dwordx4 v140, s[8:9]
	s_mov_b32 m0, s45
	s_add_i32 s46, s43, 0x6000
	global_load_lds_dwordx4 v144, s[14:15]
	s_mov_b32 m0, s46
	v_mov_b32_e32 v1, v2
	global_load_lds_dwordx4 v140, s[14:15]
	v_mov_b32_e32 v145, v2
	v_mov_b32_e32 v141, v2
	s_cmp_eq_u32 s22, 1
	v_lshl_add_u64 v[10:11], s[10:11], 0, v[142:143]
	v_lshl_add_u64 v[8:9], s[10:11], 0, v[0:1]
	v_lshl_add_u64 v[4:5], s[8:9], 0, v[144:145]
	s_cselect_b64 s[12:13], -1, 0
	s_cmp_lg_u32 s22, 1
	v_lshl_add_u64 v[6:7], s[8:9], 0, v[140:141]
	s_cbranch_scc1 .LBB0_141
	s_barrier

.Lrstd6_outer:
	s_mov_b32 s20, 0
	v_cmp_gt_i64_e32 vcc, s[14:15], v[166:167]
	s_cbranch_vccnz .Lrstd6_issued
	s_ashr_i32 s6, s14, 31
	s_lshr_b32 s6, s6, 29
	s_add_i32 s6, s14, s6
	s_ashr_i32 s7, s6, 3
	s_and_b32 s6, s6, -8
	s_sub_i32 s6, s14, s6
	s_cmp_lt_i32 s6, 0
	s_movk_i32 s16, 0x161
	s_cselect_b32 s16, s16, 0x160
	s_mul_i32 s6, s6, s16
	s_add_i32 s6, s6, s7
	s_mul_hi_i32 s7, s6, 0x2e8ba2e9
	s_lshr_b32 s16, s7, 31
	s_ashr_i32 s7, s7, 5
	s_add_i32 s7, s7, s16
	s_lshl_b32 s16, s7, 3
	s_sub_i32 s17, 0x80, s16
	s_min_i32 s17, s17, 8
	s_abs_i32 s17, s17
	v_cvt_f32_u32_e32 v3, s17
	s_sub_i32 s18, 0, s17
	s_mulk_i32 s7, 0xb0
	s_sub_i32 s6, s6, s7
	v_rcp_iflag_f32_e32 v3, v3
	s_ashr_i32 s7, s6, 31
	s_abs_i32 s6, s6
	v_mul_f32_e32 v3, 0x4f7ffffe, v3
	v_cvt_u32_f32_e32 v3, v3
	s_nop 0
	v_readfirstlane_b32 s19, v3
	s_mul_i32 s18, s18, s19
	s_mul_hi_u32 s18, s19, s18
	s_add_i32 s19, s19, s18
	s_mul_hi_u32 s18, s6, s19
	s_mul_i32 s18, s18, s17
	s_sub_i32 s6, s6, s18
	s_sub_i32 s18, s6, s17
	s_cmp_ge_u32 s6, s17
	s_cselect_b32 s6, s18, s6
	s_sub_i32 s18, s6, s17
	s_cmp_ge_u32 s6, s17
	s_cselect_b32 s6, s18, s6
	s_xor_b32 s6, s6, s7
	s_sub_i32 s6, s6, s7
	s_add_i32 s16, s16, s6
	v_lshl_add_u32 v4, s16, 8, v0
	v_ashrrev_i32_e32 v5, 31, v4
	v_lshlrev_b64 v[4:5], 6, v[4:5]
	v_lshl_add_u64 v[4:5], s[12:13], 0, v[4:5]
	global_load_dwordx4 v[24:27], v[4:5], off
	global_load_dwordx4 v[28:31], v[4:5], off offset:32
	global_load_dwordx4 v[32:35], v[4:5], off offset:16
	global_load_dwordx4 v[36:39], v[4:5], off offset:48
	s_add_u32 s14, s14, s86
	s_addc_u32 s15, s15, s87
	s_add_u32 s14, s14, s86
	s_addc_u32 s15, s15, s87
	s_add_i32 s20, s20, 1
	v_cmp_gt_i64_e32 vcc, s[14:15], v[166:167]
	s_cbranch_vccnz .Lrstd6_issued
	s_ashr_i32 s6, s14, 31
	s_lshr_b32 s6, s6, 29
	s_add_i32 s6, s14, s6
	s_ashr_i32 s7, s6, 3
	s_and_b32 s6, s6, -8
	s_sub_i32 s6, s14, s6
	s_cmp_lt_i32 s6, 0
	s_movk_i32 s16, 0x161
	s_cselect_b32 s16, s16, 0x160
	s_mul_i32 s6, s6, s16
	s_add_i32 s6, s6, s7
	s_mul_hi_i32 s7, s6, 0x2e8ba2e9
	s_lshr_b32 s16, s7, 31
	s_ashr_i32 s7, s7, 5
	s_add_i32 s7, s7, s16
	s_lshl_b32 s16, s7, 3
	s_sub_i32 s17, 0x80, s16
	s_min_i32 s17, s17, 8
	s_abs_i32 s17, s17
	v_cvt_f32_u32_e32 v3, s17
	s_sub_i32 s18, 0, s17
	s_mulk_i32 s7, 0xb0
	s_sub_i32 s6, s6, s7
	v_rcp_iflag_f32_e32 v3, v3
	s_ashr_i32 s7, s6, 31
	s_abs_i32 s6, s6
	v_mul_f32_e32 v3, 0x4f7ffffe, v3
	v_cvt_u32_f32_e32 v3, v3
	s_nop 0
	v_readfirstlane_b32 s19, v3
	s_mul_i32 s18, s18, s19
	s_mul_hi_u32 s18, s19, s18
	s_add_i32 s19, s19, s18
	s_mul_hi_u32 s18, s6, s19
	s_mul_i32 s18, s18, s17
	s_sub_i32 s6, s6, s18
	s_sub_i32 s18, s6, s17
	s_cmp_ge_u32 s6, s17
	s_cselect_b32 s6, s18, s6
	s_sub_i32 s18, s6, s17
	s_cmp_ge_u32 s6, s17
	s_cselect_b32 s6, s18, s6
	s_xor_b32 s6, s6, s7
	s_sub_i32 s6, s6, s7
	s_add_i32 s16, s16, s6
	v_lshl_add_u32 v4, s16, 8, v0
	v_ashrrev_i32_e32 v5, 31, v4
	v_lshlrev_b64 v[4:5], 6, v[4:5]
	v_lshl_add_u64 v[4:5], s[12:13], 0, v[4:5]
	global_load_dwordx4 v[40:43], v[4:5], off
	global_load_dwordx4 v[44:47], v[4:5], off offset:32
	global_load_dwordx4 v[48:51], v[4:5], off offset:16
	global_load_dwordx4 v[52:55], v[4:5], off offset:48
	s_add_u32 s14, s14, s86
	s_addc_u32 s15, s15, s87
	s_add_u32 s14, s14, s86
	s_addc_u32 s15, s15, s87
	s_add_i32 s20, s20, 1
	v_cmp_gt_i64_e32 vcc, s[14:15], v[166:167]
	s_cbranch_vccnz .Lrstd6_issued
	s_ashr_i32 s6, s14, 31
	s_lshr_b32 s6, s6, 29
	s_add_i32 s6, s14, s6
	s_ashr_i32 s7, s6, 3
	s_and_b32 s6, s6, -8
	s_sub_i32 s6, s14, s6
	s_cmp_lt_i32 s6, 0
	s_movk_i32 s16, 0x161
	s_cselect_b32 s16, s16, 0x160
	s_mul_i32 s6, s6, s16
	s_add_i32 s6, s6, s7
	s_mul_hi_i32 s7, s6, 0x2e8ba2e9
	s_lshr_b32 s16, s7, 31
	s_ashr_i32 s7, s7, 5
	s_add_i32 s7, s7, s16
	s_lshl_b32 s16, s7, 3
	s_sub_i32 s17, 0x80, s16
	s_min_i32 s17, s17, 8
	s_abs_i32 s17, s17
	v_cvt_f32_u32_e32 v3, s17
	s_sub_i32 s18, 0, s17
	s_mulk_i32 s7, 0xb0
	s_sub_i32 s6, s6, s7
	v_rcp_iflag_f32_e32 v3, v3
	s_ashr_i32 s7, s6, 31
	s_abs_i32 s6, s6
	v_mul_f32_e32 v3, 0x4f7ffffe, v3
	v_cvt_u32_f32_e32 v3, v3
	s_nop 0
	v_readfirstlane_b32 s19, v3
	s_mul_i32 s18, s18, s19
	s_mul_hi_u32 s18, s19, s18
	s_add_i32 s19, s19, s18
	s_mul_hi_u32 s18, s6, s19
	s_mul_i32 s18, s18, s17
	s_sub_i32 s6, s6, s18
	s_sub_i32 s18, s6, s17
	s_cmp_ge_u32 s6, s17
	s_cselect_b32 s6, s18, s6
	s_sub_i32 s18, s6, s17
	s_cmp_ge_u32 s6, s17
	s_cselect_b32 s6, s18, s6
	s_xor_b32 s6, s6, s7
	s_sub_i32 s6, s6, s7
	s_add_i32 s16, s16, s6
	v_lshl_add_u32 v4, s16, 8, v0
	v_ashrrev_i32_e32 v5, 31, v4
	v_lshlrev_b64 v[4:5], 6, v[4:5]
	v_lshl_add_u64 v[4:5], s[12:13], 0, v[4:5]
	global_load_dwordx4 v[56:59], v[4:5], off
	global_load_dwordx4 v[60:63], v[4:5], off offset:32
	global_load_dwordx4 v[64:67], v[4:5], off offset:16
	global_load_dwordx4 v[68:71], v[4:5], off offset:48
	s_add_u32 s14, s14, s86
	s_addc_u32 s15, s15, s87
	s_add_u32 s14, s14, s86
	s_addc_u32 s15, s15, s87
	s_add_i32 s20, s20, 1
	v_cmp_gt_i64_e32 vcc, s[14:15], v[166:167]
	s_cbranch_vccnz .Lrstd6_issued
	s_ashr_i32 s6, s14, 31
	s_lshr_b32 s6, s6, 29
	s_add_i32 s6, s14, s6
	s_ashr_i32 s7, s6, 3
	s_and_b32 s6, s6, -8
	s_sub_i32 s6, s14, s6
	s_cmp_lt_i32 s6, 0
	s_movk_i32 s16, 0x161
	s_cselect_b32 s16, s16, 0x160
	s_mul_i32 s6, s6, s16
	s_add_i32 s6, s6, s7
	s_mul_hi_i32 s7, s6, 0x2e8ba2e9
	s_lshr_b32 s16, s7, 31
	s_ashr_i32 s7, s7, 5
	s_add_i32 s7, s7, s16
	s_lshl_b32 s16, s7, 3
	s_sub_i32 s17, 0x80, s16
	s_min_i32 s17, s17, 8
	s_abs_i32 s17, s17
	v_cvt_f32_u32_e32 v3, s17
	s_sub_i32 s18, 0, s17
	s_mulk_i32 s7, 0xb0
	s_sub_i32 s6, s6, s7
	v_rcp_iflag_f32_e32 v3, v3
	s_ashr_i32 s7, s6, 31
	s_abs_i32 s6, s6
	v_mul_f32_e32 v3, 0x4f7ffffe, v3
	v_cvt_u32_f32_e32 v3, v3
	s_nop 0
	v_readfirstlane_b32 s19, v3
	s_mul_i32 s18, s18, s19
	s_mul_hi_u32 s18, s19, s18
	s_add_i32 s19, s19, s18
	s_mul_hi_u32 s18, s6, s19
	s_mul_i32 s18, s18, s17
	s_sub_i32 s6, s6, s18
	s_sub_i32 s18, s6, s17
	s_cmp_ge_u32 s6, s17
	s_cselect_b32 s6, s18, s6
	s_sub_i32 s18, s6, s17
	s_cmp_ge_u32 s6, s17
	s_cselect_b32 s6, s18, s6
	s_xor_b32 s6, s6, s7
	s_sub_i32 s6, s6, s7
	s_add_i32 s16, s16, s6
	v_lshl_add_u32 v4, s16, 8, v0
	v_ashrrev_i32_e32 v5, 31, v4
	v_lshlrev_b64 v[4:5], 6, v[4:5]
	v_lshl_add_u64 v[4:5], s[12:13], 0, v[4:5]
	global_load_dwordx4 v[72:75], v[4:5], off
	global_load_dwordx4 v[76:79], v[4:5], off offset:32
	global_load_dwordx4 v[80:83], v[4:5], off offset:16
	global_load_dwordx4 v[84:87], v[4:5], off offset:48
	s_add_u32 s14, s14, s86
	s_addc_u32 s15, s15, s87
	s_add_u32 s14, s14, s86
	s_addc_u32 s15, s15, s87
	s_add_i32 s20, s20, 1
	v_cmp_gt_i64_e32 vcc, s[14:15], v[166:167]
	s_cbranch_vccnz .Lrstd6_issued
	s_ashr_i32 s6, s14, 31
	s_lshr_b32 s6, s6, 29
	s_add_i32 s6, s14, s6
	s_ashr_i32 s7, s6, 3
	s_and_b32 s6, s6, -8
	s_sub_i32 s6, s14, s6
	s_cmp_lt_i32 s6, 0
	s_movk_i32 s16, 0x161
	s_cselect_b32 s16, s16, 0x160
	s_mul_i32 s6, s6, s16
	s_add_i32 s6, s6, s7
	s_mul_hi_i32 s7, s6, 0x2e8ba2e9
	s_lshr_b32 s16, s7, 31
	s_ashr_i32 s7, s7, 5
	s_add_i32 s7, s7, s16
	s_lshl_b32 s16, s7, 3
	s_sub_i32 s17, 0x80, s16
	s_min_i32 s17, s17, 8
	s_abs_i32 s17, s17
	v_cvt_f32_u32_e32 v3, s17
	s_sub_i32 s18, 0, s17
	s_mulk_i32 s7, 0xb0
	s_sub_i32 s6, s6, s7
	v_rcp_iflag_f32_e32 v3, v3
	s_ashr_i32 s7, s6, 31
	s_abs_i32 s6, s6
	v_mul_f32_e32 v3, 0x4f7ffffe, v3
	v_cvt_u32_f32_e32 v3, v3
	s_nop 0
	v_readfirstlane_b32 s19, v3
	s_mul_i32 s18, s18, s19
	s_mul_hi_u32 s18, s19, s18
	s_add_i32 s19, s19, s18
	s_mul_hi_u32 s18, s6, s19
	s_mul_i32 s18, s18, s17
	s_sub_i32 s6, s6, s18
	s_sub_i32 s18, s6, s17
	s_cmp_ge_u32 s6, s17
	s_cselect_b32 s6, s18, s6
	s_sub_i32 s18, s6, s17
	s_cmp_ge_u32 s6, s17
	s_cselect_b32 s6, s18, s6
	s_xor_b32 s6, s6, s7
	s_sub_i32 s6, s6, s7
	s_add_i32 s16, s16, s6
	v_lshl_add_u32 v4, s16, 8, v0
	v_ashrrev_i32_e32 v5, 31, v4
	v_lshlrev_b64 v[4:5], 6, v[4:5]
	v_lshl_add_u64 v[4:5], s[12:13], 0, v[4:5]
	global_load_dwordx4 v[88:91], v[4:5], off
	global_load_dwordx4 v[92:95], v[4:5], off offset:32
	global_load_dwordx4 v[96:99], v[4:5], off offset:16
	global_load_dwordx4 v[100:103], v[4:5], off offset:48
	s_add_u32 s14, s14, s86
	s_addc_u32 s15, s15, s87
	s_add_u32 s14, s14, s86
	s_addc_u32 s15, s15, s87
	s_add_i32 s20, s20, 1
	v_cmp_gt_i64_e32 vcc, s[14:15], v[166:167]
	s_cbranch_vccnz .Lrstd6_issued
	s_ashr_i32 s6, s14, 31
	s_lshr_b32 s6, s6, 29
	s_add_i32 s6, s14, s6
	s_ashr_i32 s7, s6, 3
	s_and_b32 s6, s6, -8
	s_sub_i32 s6, s14, s6
	s_cmp_lt_i32 s6, 0
	s_movk_i32 s16, 0x161
	s_cselect_b32 s16, s16, 0x160
	s_mul_i32 s6, s6, s16
	s_add_i32 s6, s6, s7
	s_mul_hi_i32 s7, s6, 0x2e8ba2e9
	s_lshr_b32 s16, s7, 31
	s_ashr_i32 s7, s7, 5
	s_add_i32 s7, s7, s16
	s_lshl_b32 s16, s7, 3
	s_sub_i32 s17, 0x80, s16
	s_min_i32 s17, s17, 8
	s_abs_i32 s17, s17
	v_cvt_f32_u32_e32 v3, s17
	s_sub_i32 s18, 0, s17
	s_mulk_i32 s7, 0xb0
	s_sub_i32 s6, s6, s7
	v_rcp_iflag_f32_e32 v3, v3
	s_ashr_i32 s7, s6, 31
	s_abs_i32 s6, s6
	v_mul_f32_e32 v3, 0x4f7ffffe, v3
	v_cvt_u32_f32_e32 v3, v3
	s_nop 0
	v_readfirstlane_b32 s19, v3
	s_mul_i32 s18, s18, s19
	s_mul_hi_u32 s18, s19, s18
	s_add_i32 s19, s19, s18
	s_mul_hi_u32 s18, s6, s19
	s_mul_i32 s18, s18, s17
	s_sub_i32 s6, s6, s18
	s_sub_i32 s18, s6, s17
	s_cmp_ge_u32 s6, s17
	s_cselect_b32 s6, s18, s6
	s_sub_i32 s18, s6, s17
	s_cmp_ge_u32 s6, s17
	s_cselect_b32 s6, s18, s6
	s_xor_b32 s6, s6, s7
	s_sub_i32 s6, s6, s7
	s_add_i32 s16, s16, s6
	v_lshl_add_u32 v4, s16, 8, v0
	v_ashrrev_i32_e32 v5, 31, v4
	v_lshlrev_b64 v[4:5], 6, v[4:5]
	v_lshl_add_u64 v[4:5], s[12:13], 0, v[4:5]
	global_load_dwordx4 v[104:107], v[4:5], off
	global_load_dwordx4 v[108:111], v[4:5], off offset:32
	global_load_dwordx4 v[112:115], v[4:5], off offset:16
	global_load_dwordx4 v[116:119], v[4:5], off offset:48
	s_add_u32 s14, s14, s86
	s_addc_u32 s15, s15, s87
	s_add_u32 s14, s14, s86
	s_addc_u32 s15, s15, s87
	s_add_i32 s20, s20, 1
.Lrstd6_issued:
	s_waitcnt vmcnt(0)
	s_cmp_le_u32 s20, 0
	s_cbranch_scc1 .Lrstd6_done
	v_add_f32_e32 v24, v24, v25
	v_add_f32_e32 v26, v26, v27
	v_add_f32_e32 v28, v28, v29
	v_add_f32_e32 v30, v30, v31
	v_add_f32_e32 v32, v32, v33
	v_add_f32_e32 v34, v34, v35
	v_add_f32_e32 v36, v36, v37
	v_add_f32_e32 v38, v38, v39
	v_add_f32_e32 v24, v24, v26
	v_add_f32_e32 v28, v28, v30
	v_add_f32_e32 v32, v32, v34
	v_add_f32_e32 v36, v36, v38
	v_add_f32_e32 v24, v24, v32
	v_add_f32_e32 v28, v28, v36
	v_add_f32_e32 v3, v24, v28
	v_fmamk_f32 v3, v3, 0x3a800000, v209
	v_mul_f32_e32 v4, 0x4b800000, v3
	v_cmp_gt_f32_e32 vcc, s68, v3
	s_nop 1
	v_cndmask_b32_e32 v3, v3, v4, vcc
	v_rsq_f32_e32 v3, v3
	s_nop 0
	v_mul_f32_e32 v4, 0x45800000, v3
	v_cndmask_b32_e32 v3, v3, v4, vcc
	ds_write_b32 v1, v3
	v_add_u32_e32 v1, 0x800, v1
	s_cmp_le_u32 s20, 1
	s_cbranch_scc1 .Lrstd6_done
	v_add_f32_e32 v40, v40, v41
	v_add_f32_e32 v42, v42, v43
	v_add_f32_e32 v44, v44, v45
	v_add_f32_e32 v46, v46, v47
	v_add_f32_e32 v48, v48, v49
	v_add_f32_e32 v50, v50, v51
	v_add_f32_e32 v52, v52, v53
	v_add_f32_e32 v54, v54, v55
	v_add_f32_e32 v40, v40, v42
	v_add_f32_e32 v44, v44, v46
	v_add_f32_e32 v48, v48, v50
	v_add_f32_e32 v52, v52, v54
	v_add_f32_e32 v40, v40, v48
	v_add_f32_e32 v44, v44, v52
	v_add_f32_e32 v3, v40, v44
	v_fmamk_f32 v3, v3, 0x3a800000, v209
	v_mul_f32_e32 v4, 0x4b800000, v3
	v_cmp_gt_f32_e32 vcc, s68, v3
	s_nop 1
	v_cndmask_b32_e32 v3, v3, v4, vcc
	v_rsq_f32_e32 v3, v3
	s_nop 0
	v_mul_f32_e32 v4, 0x45800000, v3
	v_cndmask_b32_e32 v3, v3, v4, vcc
	ds_write_b32 v1, v3
	v_add_u32_e32 v1, 0x800, v1
	s_cmp_le_u32 s20, 2
	s_cbranch_scc1 .Lrstd6_done
	v_add_f32_e32 v56, v56, v57
	v_add_f32_e32 v58, v58, v59
	v_add_f32_e32 v60, v60, v61
	v_add_f32_e32 v62, v62, v63
	v_add_f32_e32 v64, v64, v65
	v_add_f32_e32 v66, v66, v67
	v_add_f32_e32 v68, v68, v69
	v_add_f32_e32 v70, v70, v71
	v_add_f32_e32 v56, v56, v58
	v_add_f32_e32 v60, v60, v62
	v_add_f32_e32 v64, v64, v66
	v_add_f32_e32 v68, v68, v70
	v_add_f32_e32 v56, v56, v64
	v_add_f32_e32 v60, v60, v68
	v_add_f32_e32 v3, v56, v60
	v_fmamk_f32 v3, v3, 0x3a800000, v209
	v_mul_f32_e32 v4, 0x4b800000, v3
	v_cmp_gt_f32_e32 vcc, s68, v3
	s_nop 1
	v_cndmask_b32_e32 v3, v3, v4, vcc
	v_rsq_f32_e32 v3, v3
	s_nop 0
	v_mul_f32_e32 v4, 0x45800000, v3
	v_cndmask_b32_e32 v3, v3, v4, vcc
	ds_write_b32 v1, v3
	v_add_u32_e32 v1, 0x800, v1
	s_cmp_le_u32 s20, 3
	s_cbranch_scc1 .Lrstd6_done
	v_add_f32_e32 v72, v72, v73
	v_add_f32_e32 v74, v74, v75
	v_add_f32_e32 v76, v76, v77
	v_add_f32_e32 v78, v78, v79
	v_add_f32_e32 v80, v80, v81
	v_add_f32_e32 v82, v82, v83
	v_add_f32_e32 v84, v84, v85
	v_add_f32_e32 v86, v86, v87
	v_add_f32_e32 v72, v72, v74
	v_add_f32_e32 v76, v76, v78
	v_add_f32_e32 v80, v80, v82
	v_add_f32_e32 v84, v84, v86
	v_add_f32_e32 v72, v72, v80
	v_add_f32_e32 v76, v76, v84
	v_add_f32_e32 v3, v72, v76
	v_fmamk_f32 v3, v3, 0x3a800000, v209
	v_mul_f32_e32 v4, 0x4b800000, v3
	v_cmp_gt_f32_e32 vcc, s68, v3
	s_nop 1
	v_cndmask_b32_e32 v3, v3, v4, vcc
	v_rsq_f32_e32 v3, v3
	s_nop 0
	v_mul_f32_e32 v4, 0x45800000, v3
	v_cndmask_b32_e32 v3, v3, v4, vcc
	ds_write_b32 v1, v3
	v_add_u32_e32 v1, 0x800, v1
	s_cmp_le_u32 s20, 4
	s_cbranch_scc1 .Lrstd6_done
	v_add_f32_e32 v88, v88, v89
	v_add_f32_e32 v90, v90, v91
	v_add_f32_e32 v92, v92, v93
	v_add_f32_e32 v94, v94, v95
	v_add_f32_e32 v96, v96, v97
	v_add_f32_e32 v98, v98, v99
	v_add_f32_e32 v100, v100, v101
	v_add_f32_e32 v102, v102, v103
	v_add_f32_e32 v88, v88, v90
	v_add_f32_e32 v92, v92, v94
	v_add_f32_e32 v96, v96, v98
	v_add_f32_e32 v100, v100, v102
	v_add_f32_e32 v88, v88, v96
	v_add_f32_e32 v92, v92, v100
	v_add_f32_e32 v3, v88, v92
	v_fmamk_f32 v3, v3, 0x3a800000, v209
	v_mul_f32_e32 v4, 0x4b800000, v3
	v_cmp_gt_f32_e32 vcc, s68, v3
	s_nop 1
	v_cndmask_b32_e32 v3, v3, v4, vcc
	v_rsq_f32_e32 v3, v3
	s_nop 0
	v_mul_f32_e32 v4, 0x45800000, v3
	v_cndmask_b32_e32 v3, v3, v4, vcc
	ds_write_b32 v1, v3
	v_add_u32_e32 v1, 0x800, v1
	s_cmp_le_u32 s20, 5
	s_cbranch_scc1 .Lrstd6_done
	v_add_f32_e32 v104, v104, v105
	v_add_f32_e32 v106, v106, v107
	v_add_f32_e32 v108, v108, v109
	v_add_f32_e32 v110, v110, v111
	v_add_f32_e32 v112, v112, v113
	v_add_f32_e32 v114, v114, v115
	v_add_f32_e32 v116, v116, v117
	v_add_f32_e32 v118, v118, v119
	v_add_f32_e32 v104, v104, v106
	v_add_f32_e32 v108, v108, v110
	v_add_f32_e32 v112, v112, v114
	v_add_f32_e32 v116, v116, v118
	v_add_f32_e32 v104, v104, v112
	v_add_f32_e32 v108, v108, v116
	v_add_f32_e32 v3, v104, v108
	v_fmamk_f32 v3, v3, 0x3a800000, v209
	v_mul_f32_e32 v4, 0x4b800000, v3
	v_cmp_gt_f32_e32 vcc, s68, v3
	s_nop 1
	v_cndmask_b32_e32 v3, v3, v4, vcc
	v_rsq_f32_e32 v3, v3
	s_nop 0
	v_mul_f32_e32 v4, 0x45800000, v3
	v_cndmask_b32_e32 v3, v3, v4, vcc
	ds_write_b32 v1, v3
	v_add_u32_e32 v1, 0x800, v1
	s_branch .Lrstd6_outer
.Lrstd6_done:
.LBB0_670:
	s_or_b64 exec, exec, s[10:11]
	v_readlane_b32 s10, v254, 12
	s_mov_b64 s[14:15], s[84:85]
	s_mov_b64 s[16:17], s[84:85]
	v_mov_b32_e32 v3, v208
	v_readlane_b32 s11, v254, 13
	s_waitcnt lgkmcnt(0)
	s_barrier
	s_and_b64 vcc, exec, s[10:11]
	v_readfirstlane_b32 s7, v3
	s_cbranch_vccz .LBB0_756
	v_lshlrev_b32_e32 v1, 4, v3
	v_add_u32_e32 v0, 0x2000, v1
	v_ashrrev_i32_e32 v4, 31, v0
	v_lshrrev_b32_e32 v4, 22, v4
	v_add_u32_e32 v4, v0, v4
	v_ashrrev_i32_e32 v12, 10, v4
	v_mul_i32_i24_e32 v4, 0x400, v12
	v_sub_u32_e32 v0, v0, v4
	v_lshrrev_b32_e32 v4, 4, v0
	s_ashr_i32 s18, s7, 6
	v_bitop3_b32 v0, v4, v0, 32 bitop3:0x6c
	s_ashr_i32 s6, s7, 8
	s_lshl_b32 s54, s18, 10
	v_ashrrev_i32_e32 v4, 31, v0
	s_add_u32 s19, s8, 0x3e00000
	v_lshrrev_b32_e32 v4, 26, v4
	s_addc_u32 s93, s9, 0
	s_mul_i32 s10, s36, 0xb00000
	v_add_u32_e32 v4, v0, v4
	v_lshlrev_b32_e32 v5, 3, v12
	s_add_u32 s10, s8, s10
	v_ashrrev_i32_e32 v13, 6, v4
	v_and_b32_e32 v5, -16, v5
	s_addc_u32 s11, s9, 0
	v_add_u32_e32 v5, v13, v5
	s_add_u32 s55, s10, 0xe00000
	v_and_b32_e32 v6, 3, v13
	s_mov_b32 s10, 0x1fffe0
	v_lshrrev_b32_e32 v7, 2, v5
	v_lshlrev_b32_e32 v8, 1, v5
	v_and_b32_e32 v4, 0xc0, v4
	v_and_or_b32 v6, v5, s10, v6
	v_and_b32_e32 v7, 4, v7
	v_and_b32_e32 v8, 24, v8
	v_sub_u32_e32 v0, v0, v4
	v_or3_b32 v6, v6, v7, v8
	v_lshlrev_b32_e32 v7, 5, v12
	v_ashrrev_i16_sdwa v0, v210, sext(v0) dst_sel:DWORD dst_unused:UNUSED_PAD src0_sel:DWORD src1_sel:BYTE_0
	v_and_b32_e32 v7, 32, v7
	v_bfe_i32 v14, v0, 0, 16
	v_add_lshl_u32 v4, v7, v14, 1
	v_lshl_add_u32 v0, v6, 11, v4
	v_and_b32_e32 v18, 15, v5
	v_bfe_u32 v19, v5, 4, 2
	v_lshl_or_b32 v18, v18, 2, v19
	v_and_b32_e32 v19, 64, v5
	v_or_b32_e32 v18, v18, v19
	v_lshl_add_u32 v170, v18, 11, v4
	v_bfe_i32 v4, v3, 27, 1
	v_lshrrev_b32_e32 v4, 22, v4
	v_add_u32_e32 v4, v1, v4
	v_and_b32_e32 v4, 0xfffffc00, v4
	v_sub_u32_e32 v1, v1, v4
	v_lshrrev_b32_e32 v4, 4, v1
	v_ashrrev_i32_e32 v5, 31, v3
	v_bitop3_b32 v1, v4, v1, 32 bitop3:0x6c
	v_lshrrev_b32_e32 v5, 26, v5
	v_ashrrev_i32_e32 v4, 31, v1
	v_add_u32_e32 v5, v3, v5
	v_lshrrev_b32_e32 v4, 26, v4
	v_ashrrev_i32_e32 v16, 6, v5
	v_add_u32_e32 v4, v1, v4
	v_lshlrev_b32_e32 v5, 3, v16
	v_ashrrev_i32_e32 v15, 6, v4
	v_and_b32_e32 v5, -16, v5
	v_add_u32_e32 v5, v15, v5
	v_and_b32_e32 v6, 3, v15
	v_lshrrev_b32_e32 v7, 2, v5
	v_lshlrev_b32_e32 v8, 1, v5
	v_and_b32_e32 v4, 0xc0, v4
	v_writelane_b32 v253, s70, 17
	v_and_or_b32 v6, v5, s10, v6
	v_and_b32_e32 v7, 4, v7
	v_and_b32_e32 v8, 24, v8
	v_sub_u32_e32 v1, v1, v4
	v_writelane_b32 v253, s71, 18
	s_addc_u32 s70, s11, 0
	v_or3_b32 v6, v6, v7, v8
	v_lshlrev_b32_e32 v7, 5, v16
	v_ashrrev_i16_sdwa v1, v210, sext(v1) dst_sel:DWORD dst_unused:UNUSED_PAD src0_sel:DWORD src1_sel:BYTE_0
	v_readlane_b32 s10, v254, 37
	v_and_b32_e32 v7, 32, v7
	v_bfe_i32 v17, v1, 0, 16
	v_readlane_b32 s11, v254, 38
	s_add_u32 s12, s55, s10
	v_add_lshl_u32 v1, v7, v17, 1
	s_addc_u32 s13, s70, s11
	s_add_i32 s71, s54, 0
	v_lshl_add_u32 v172, v6, 11, v1
	s_add_i32 m0, s71, 0x10000
	v_and_b32_e32 v18, 15, v5
	v_bfe_u32 v19, v5, 4, 2
	v_lshl_or_b32 v18, v18, 2, v19
	v_and_b32_e32 v19, 64, v5
	v_or_b32_e32 v18, v18, v19
	v_lshl_add_u32 v174, v18, 11, v1
	global_load_lds_dwordx4 v172, s[12:13]
	s_add_i32 m0, s71, 0x12000
	s_add_u32 s10, s12, 0x40000
	global_load_lds_dwordx4 v0, s[12:13]
	s_addc_u32 s11, s13, 0
	s_add_i32 m0, s71, 0x14000
	v_writelane_b32 v253, s19, 11
	global_load_lds_dwordx4 v172, s[10:11]
	s_add_i32 m0, s71, 0x16000
	v_mov_b32_e32 v173, v2
	global_load_lds_dwordx4 v0, s[10:11]
	v_readlane_b32 s10, v254, 35
	v_readlane_b32 s11, v254, 36
	s_add_u32 s10, s19, s10
	s_addc_u32 s11, s93, s11
	s_add_i32 s72, s71, 0x2000
	s_mov_b32 m0, s71
	s_add_u32 s20, s10, 0x40000
	global_load_lds_dwordx4 v174, s[10:11]
	s_mov_b32 m0, s72
	s_addc_u32 s21, s11, 0
	s_add_i32 s73, s71, 0x4000
	global_load_lds_dwordx4 v170, s[10:11]
	s_mov_b32 m0, s73
	s_add_i32 s78, s71, 0x6000
	global_load_lds_dwordx4 v174, s[20:21]
	s_mov_b32 m0, s78
	s_cmp_eq_u32 s6, 1
	global_load_lds_dwordx4 v170, s[20:21]
	s_load_dwordx2 s[14:15], s[14:15], 0x60
	s_nop 0
	s_load_dwordx2 s[16:17], s[16:17], 0x68
	v_mov_b32_e32 v1, v2
	v_mov_b32_e32 v175, v2
	v_mov_b32_e32 v171, v2
	s_cselect_b64 s[20:21], -1, 0
	v_lshl_add_u64 v[8:9], s[12:13], 0, v[172:173]
	v_lshl_add_u64 v[6:7], s[12:13], 0, v[0:1]
	v_lshl_add_u64 v[4:5], s[10:11], 0, v[174:175]
	v_writelane_b32 v253, s20, 13
	s_cmp_lg_u32 s6, 1
	v_lshl_add_u64 v[10:11], s[10:11], 0, v[170:171]
	v_writelane_b32 v253, s21, 14
	s_cbranch_scc1 .LBB0_673
	s_barrier
